# combo1 + exact vmcnt counts for map-A waves at the next unit's load waits (skip own store acks)
# baseline (speedup 1.0000x reference)
; __device__ __forceinline__ void diff_phase(LAS unsigned char* lds, int L) {
;     ...
;         if (!(ui & 1)) {
;             if (tid < 320) { const int d = 207 - tid; float v = 0.f;
;                 if (d < 0) v = -INFINITY;
;                 else if (d < 128) { int bk = d;
;                     if (d >= 16) { bk = 16 + (int)(__builtin_amdgcn_logf((float)d * 0.0625f) * (16.0f / 3.0f)); bk = bk > 31 ? 31 : bk; }
;                     v = (P->rel_bias[bk * 8 + hj] - P->rel_bias[31 * 8 + hj]) * LOG2E; }
;                 dtab[tid] = v; }
.Ldf_p2:
	s_and_b64 vcc, exec, s[22:23]
	s_cselect_b32 s101, s100, 0
	s_bitcmp1_b32 s43, 0
	s_cbranch_scc1 .Ldf_p2_notab
	s_and_saveexec_b64 s[30:31], s[4:5]
	s_cbranch_execz .Ldf_t2_skip
	v_mov_b32_e32 v0, v218
	s_and_saveexec_b64 s[48:49], s[6:7]
	s_cbranch_execz .Ldf_t2_in_skip
	s_cmp_lg_u32 s101, 0
	s_cbranch_scc1 .Ldf_t2_wa
	s_waitcnt vmcnt(12)
	s_branch .Ldf_t2_wd
.Ldf_t2_wa:
	s_waitcnt vmcnt(28)
.Ldf_t2_wd:
	v_sub_f32_e32 v0, v236, v237
	v_mul_f32_e32 v0, 0x3fb8aa3b, v0

; #define LAS __attribute__((address_space(3)))
; #define DF_LOAD(T) do { const bf16* kg = Kb + (tokb + 128 * (T) + krow0) * 1024 + kgcol; const bf16* vg = Vb + (tokb + 128 * (T) + vkey0) * 1024 + vgcol; \
;         _Pragma("unroll") for (int c_ = 0; c_ < 4; ++c_) { kreg[c_] = *(const u32x4*)(kg + c_ * 8 * 1024); vreg[c_] = *(const u32x4*)(vg + c_ * 16 * 1024); } } while (0)
; #define DF_STORE(sb) do { LAS unsigned char* s_ = lds + (sb) * DST; \
;         _Pragma("unroll") for (int c_ = 0; c_ < 4; ++c_) { *(LAS u32x4*)(s_ + klds + c_ * 8 * 144) = kreg[c_]; *(LAS u32x4*)(s_ + vlds + c_ * 1024) = vreg[c_]; } } while (0)
; __device__ __forceinline__ void diff_phase(LAS unsigned char* lds, int L) {
;     ...
;         DF_LOAD(NT - 1); DF_STORE(0);
;         __syncthreads();
;         asm volatile("" :: "v"(qr[0]), "v"(qr[1]), "v"(qr[2]), "v"(qr[3]));
;         for (int it = 0; it < NT; ++it) {
;             const int T = NT - 1 - it;
;             if (it + 1 < NT) DF_LOAD(T - 1);
;             LAS const unsigned char* st = lds + (it & 1) * DST; LAS const unsigned char* kst = st + map * DKS;
;             if (2 * T + 1 <= th) tile_compute<MODE_DIFF, 4>(o, negm, m, thr, l, R, qr, nullptr, kst + 64 * 144, st + DVO + 16384, 128 * T + 64, qw0, r32, hi, lane, dtab);
;             if (2 * T <= th) tile_compute<MODE_DIFF, 4>(o, negm, m, thr, l, R, qr, nullptr, kst, st + DVO, 128 * T, qw0, r32, hi, lane, dtab);
;             if (it + 1 < NT) DF_STORE((it + 1) & 1);
;             __syncthreads();
.Ldf_p2_notab:
	v_add_u32_e32 v6, s45, v219
	v_or_b32_e32 v0, s45, v220
	s_lshl_b32 s49, s35, 9
	s_lshl_b64 s[28:29], s[28:29], 22
	s_lshl_b32 s3, s35, 18
	v_mov_b32_e32 v1, v2
	v_add_u32_e32 v3, 0, v207
	v_add_u32_e32 v8, 0, v204
	v_ashrrev_i32_e32 v7, 31, v6
	v_lshlrev_b32_e32 v0, 1, v0
	s_lshr_b32 s48, s46, 6
	s_addk_i32 s49, 0x200
	s_or_b32 s3, s28, s3
	v_mov_b32_e32 v14, v2
	v_mov_b32_e32 v15, v2
	v_lshl_add_u64 v[190:191], v[6:7], 1, v[182:183]
	v_lshl_add_u64 v[192:193], v[184:185], 0, v[0:1]
	v_lshlrev_b64 v[188:189], 10, v[4:5]
	s_add_u32 s28, s10, s3
	v_mov_b32_e32 v0, v2
	v_mov_b32_e32 v4, v2
	v_mov_b32_e32 v5, v2
	v_mov_b32_e32 v6, v2
	v_mov_b32_e32 v7, v2
	v_mov_b32_e32 v9, v2
	v_mov_b32_e32 v10, v2
	v_mov_b32_e32 v11, v2
	v_mov_b32_e32 v12, v2
	v_mov_b32_e32 v13, v2
	s_mov_b32 s47, 0
	s_addc_u32 s29, s11, s29
	s_lshl_b32 s50, s35, 1
	s_add_i32 s51, s44, 0xf0
	s_mov_b32 s53, 0xff800000
	s_cmp_lg_u32 s101, 0
	s_cbranch_scc1 .Ldf_p2_wa
	s_waitcnt vmcnt(11)
	ds_write_b128 v3, v[128:131]
	s_waitcnt vmcnt(10)
	ds_write_b128 v8, v[132:135] offset:36864
	s_waitcnt vmcnt(9)
	ds_write_b128 v3, v[140:143] offset:1152
	s_waitcnt vmcnt(8)
	ds_write_b128 v8, v[156:159] offset:37888
	s_waitcnt vmcnt(7)
	ds_write_b128 v3, v[160:163] offset:2304
	s_waitcnt vmcnt(6)
	ds_write_b128 v8, v[164:167] offset:38912
	s_waitcnt vmcnt(5)
	ds_write_b128 v3, v[168:171] offset:3456
	s_waitcnt vmcnt(4)
	ds_write_b128 v8, v[172:175] offset:39936
	s_branch .Ldf_p2_wd
.Ldf_p2_wa:
	s_waitcnt vmcnt(27)
	ds_write_b128 v3, v[128:131]
	s_waitcnt vmcnt(26)
	ds_write_b128 v8, v[132:135] offset:36864
	s_waitcnt vmcnt(25)
	ds_write_b128 v3, v[140:143] offset:1152
	s_waitcnt vmcnt(24)
	ds_write_b128 v8, v[156:159] offset:37888
	s_waitcnt vmcnt(23)
	ds_write_b128 v3, v[160:163] offset:2304
	s_waitcnt vmcnt(22)
	ds_write_b128 v8, v[164:167] offset:38912
	s_waitcnt vmcnt(21)
	ds_write_b128 v3, v[168:171] offset:3456
	s_waitcnt vmcnt(20)
	ds_write_b128 v8, v[172:175] offset:39936
.Ldf_p2_wd:
	v_mov_b32_e32 v3, v2
	v_mov_b32_e32 v8, v2
	v_mov_b64_e32 v[78:79], v[14:15]
	v_mov_b64_e32 v[62:63], v[14:15]
	v_mov_b64_e32 v[46:47], v[14:15]
	v_mov_b64_e32 v[30:31], v[14:15]
	v_mov_b64_e32 v[94:95], v[14:15]
	v_mov_b32_e32 v187, 0
	v_mov_b64_e32 v[76:77], v[12:13]
	v_mov_b64_e32 v[74:75], v[10:11]
	v_mov_b64_e32 v[72:73], v[8:9]
	v_mov_b64_e32 v[70:71], v[6:7]
	v_mov_b64_e32 v[68:69], v[4:5]
	v_mov_b64_e32 v[66:67], v[2:3]
	v_mov_b64_e32 v[64:65], v[0:1]
	v_mov_b64_e32 v[60:61], v[12:13]
	v_mov_b64_e32 v[58:59], v[10:11]
	v_mov_b64_e32 v[56:57], v[8:9]
	v_mov_b64_e32 v[54:55], v[6:7]
	v_mov_b64_e32 v[52:53], v[4:5]
	v_mov_b64_e32 v[50:51], v[2:3]
	v_mov_b64_e32 v[48:49], v[0:1]
	v_mov_b64_e32 v[44:45], v[12:13]
	v_mov_b64_e32 v[42:43], v[10:11]
	v_mov_b64_e32 v[40:41], v[8:9]
	v_mov_b64_e32 v[38:39], v[6:7]
	v_mov_b64_e32 v[36:37], v[4:5]
	v_mov_b64_e32 v[34:35], v[2:3]
	v_mov_b64_e32 v[32:33], v[0:1]
	v_mov_b64_e32 v[28:29], v[12:13]
	v_mov_b64_e32 v[26:27], v[10:11]
	v_mov_b64_e32 v[24:25], v[8:9]
	v_mov_b64_e32 v[22:23], v[6:7]
	v_mov_b64_e32 v[20:21], v[4:5]
	v_mov_b64_e32 v[18:19], v[2:3]
	v_mov_b64_e32 v[16:17], v[0:1]
	s_mov_b32 s52, 0
	v_mov_b64_e32 v[92:93], v[12:13]
	v_mov_b64_e32 v[90:91], v[10:11]
	v_mov_b64_e32 v[88:89], v[8:9]
	v_mov_b64_e32 v[86:87], v[6:7]
	v_mov_b64_e32 v[84:85], v[4:5]
	v_mov_b64_e32 v[82:83], v[2:3]
	v_mov_b64_e32 v[80:81], v[0:1]
	v_mov_b32_e32 v3, 0
	s_waitcnt lgkmcnt(0)
	s_barrier
	s_cmp_lg_u32 s101, 0
	s_cbranch_scc1 .Ldf_p2_qa
	s_waitcnt vmcnt(0)
	s_branch .Ldf_p2_qd
.Ldf_p2_qa:
	s_waitcnt vmcnt(16)
.Ldf_p2_qd:
	s_branch .LBB0_186
.LBB0_185:
	s_addk_i32 s47, 0xfe00
	s_add_i32 s3, s49, s47
	s_add_u32 s28, s28, 0xfffc0000
	s_addc_u32 s29, s29, -1
	s_add_i32 s50, s50, -2
	s_addk_i32 s51, 0xff80
	s_cmp_eq_u32 s3, 0
	s_waitcnt lgkmcnt(0)
	s_barrier
	s_cbranch_scc1 .LBB0_206
